# PEER query GEMM second half (all trips but the last): end-of-trip LDS writes issued one per MFMA from the 9th MFMA on behind one vmcnt(8); last trip keeps the compiled half
# baseline (speedup 1.0000x reference)
.LBB0_1853:
	s_and_b64 vcc, exec, s[8:9]
	s_cbranch_vccz .Lqs1853_last
	s_setprio 2
	ds_read_b128 v[194:197], v164 offset:55296
	ds_read_b128 v[224:227], v189 offset:18432
	ds_read_b128 v[228:231], v189 offset:23040
	ds_read_b128 v[232:235], v189 offset:27648
	ds_read_b128 v[236:239], v189 offset:32256
	s_andn2_b64 vcc, exec, s[8:9]
	ds_read_b128 v[240:243], v164 offset:55328
	ds_read_b128 v[190:193], v189 offset:18464
	s_waitcnt lgkmcnt(5)
	v_mfma_f32_32x32x16_bf16 v[0:15], v[224:227], v[194:197], v[0:15]
	ds_read_b128 v[198:201], v189 offset:23072
	s_waitcnt lgkmcnt(5)
	v_mfma_f32_32x32x16_bf16 v[16:31], v[228:231], v[194:197], v[16:31]
	ds_read_b128 v[224:227], v189 offset:27680
	s_waitcnt lgkmcnt(5)
	v_mfma_f32_32x32x16_bf16 v[34:49], v[232:235], v[194:197], v[34:49]
	ds_read_b128 v[228:231], v189 offset:32288
	s_waitcnt lgkmcnt(5)
	v_mfma_f32_32x32x16_bf16 v[50:65], v[236:239], v[194:197], v[50:65]
	ds_read_b128 v[194:197], v164 offset:55360
	ds_read_b128 v[232:235], v189 offset:18496
	s_waitcnt lgkmcnt(5)
	v_mfma_f32_32x32x16_bf16 v[0:15], v[190:193], v[240:243], v[0:15]
	ds_read_b128 v[236:239], v189 offset:23104
	s_waitcnt lgkmcnt(5)
	v_mfma_f32_32x32x16_bf16 v[16:31], v[198:201], v[240:243], v[16:31]
	ds_read_b128 v[190:193], v189 offset:27712
	s_waitcnt lgkmcnt(5)
	v_mfma_f32_32x32x16_bf16 v[34:49], v[224:227], v[240:243], v[34:49]
	ds_read_b128 v[198:201], v189 offset:32320
	s_waitcnt lgkmcnt(5)
	v_mfma_f32_32x32x16_bf16 v[50:65], v[228:231], v[240:243], v[50:65]
	ds_read_b128 v[240:243], v164 offset:55392
	ds_read_b128 v[224:227], v189 offset:18528
	s_waitcnt lgkmcnt(5)
	v_mfma_f32_32x32x16_bf16 v[0:15], v[232:235], v[194:197], v[0:15]
	s_waitcnt vmcnt(8)
	ds_write_b128 v166, v[66:69]
	ds_read_b128 v[228:231], v189 offset:23136
	s_waitcnt lgkmcnt(6)
	v_mfma_f32_32x32x16_bf16 v[16:31], v[236:239], v[194:197], v[16:31]
	ds_write_b128 v166, v[78:81] offset:36864
	ds_read_b128 v[232:235], v189 offset:27744
	s_waitcnt lgkmcnt(7)
	v_mfma_f32_32x32x16_bf16 v[34:49], v[190:193], v[194:197], v[34:49]
	ds_write_b128 v166, v[70:73] offset:4608
	ds_read_b128 v[236:239], v189 offset:32352
	s_waitcnt lgkmcnt(8)
	v_mfma_f32_32x32x16_bf16 v[50:65], v[198:201], v[194:197], v[50:65]
	ds_write_b128 v166, v[74:77] offset:41472
	s_waitcnt lgkmcnt(7)
	v_mfma_f32_32x32x16_bf16 v[0:15], v[224:227], v[240:243], v[0:15]
	ds_write_b128 v166, v[86:89] offset:9216
	s_waitcnt lgkmcnt(6)
	v_mfma_f32_32x32x16_bf16 v[16:31], v[228:231], v[240:243], v[16:31]
	ds_write_b128 v166, v[82:85] offset:46080
	s_waitcnt lgkmcnt(5)
	v_mfma_f32_32x32x16_bf16 v[34:49], v[232:235], v[240:243], v[34:49]
	ds_write_b128 v166, v[94:97] offset:13824
	s_waitcnt lgkmcnt(4)
	v_mfma_f32_32x32x16_bf16 v[50:65], v[236:239], v[240:243], v[50:65]
	ds_write_b128 v166, v[90:93] offset:50688
	s_setprio 0
	s_branch .LBB0_1848
